# grid barrier: first-arriving workgroup of each XCD issues one early L2 write-back while it waits (9 of the 11 layer seams)
# baseline (speedup 1.0000x reference)
; __device__ __forceinline__ unsigned xb_ld(unsigned* p)              { return __hip_atomic_load(p, __ATOMIC_RELAXED, __HIP_MEMORY_SCOPE_AGENT); }
; __device__ __forceinline__ unsigned xb_add(unsigned* p, unsigned v) { return __hip_atomic_fetch_add(p, v, __ATOMIC_RELAXED, __HIP_MEMORY_SCOPE_AGENT); }
; #define XB_SPIN(cond, bar) do { unsigned _sp = 0; while (cond) { __builtin_amdgcn_s_sleep(1); \
;     if ((++_sp & 255u) == 0u) { if (xb_ld(&(bar)[XB_TMO])) break; if (_sp > XB_SPIN_CAP) { atomicAdd(&(bar)[XB_TMO], 1u); break; } } } } while (0)
; __device__ __forceinline__ void xcd_barrier(const XcdBarrier& b) {
;     asm volatile("s_waitcnt vmcnt(0)" ::: "memory");
;     __syncthreads();
;     if (threadIdx.x == 0) {
;         unsigned* bar = b.bar;
;         __builtin_amdgcn_s_waitcnt(0);
;         unsigned nloc = b.st[0], nx = b.st[1];
;         if (nloc == 0u) { xcd_barrier_complete(bar, b.x, nloc, nx); b.st[0] = nloc; b.st[1] = nx; }
;         const unsigned old = xb_add(&bar[XB_XSUB(b.x)], 1u);
;         const unsigned gen = old / nloc;
;         if (old + 1u == (gen + 1u) * nloc) {
;             __builtin_amdgcn_fence(__ATOMIC_RELEASE, "agent");
;             asm volatile("s_waitcnt vmcnt(0)" ::: "memory");
;             const unsigned og = xb_add(&bar[XB_TOP], 1u);
;             const unsigned tg = og / nx;
;             if (og + 1u == (tg + 1u) * nx) xb_add(&bar[XB_TOPGEN], 1u);
;             else XB_SPIN(xb_ld(&bar[XB_TOPGEN]) == tg, bar);
;             __builtin_amdgcn_fence(__ATOMIC_ACQUIRE, "agent");
;             xb_add(&bar[XB_XGEN(b.x)], 1u);
;             asm volatile("s_waitcnt vmcnt(0)" ::: "memory");
;         } else {
;             XB_SPIN(xb_ld(&bar[XB_XGEN(b.x)]) == gen, bar);
.LBB0_317:
	v_readlane_b32 s4, v253, 44
	s_lshl_b32 s4, s4, 2
	s_add_u32 s37, s2, s4
	s_addc_u32 s36, s3, 0
	v_mov_b32_e32 v1, s37
	v_add_co_u32_e32 v6, vcc, 0x1000, v1
	v_mov_b32_e32 v1, s36
	s_nop 0
	v_addc_co_u32_e32 v7, vcc, 0, v1, vcc
	flat_atomic_add v3, v[6:7], v226 offset:1024 sc0
	v_cvt_f32_u32_e32 v1, v4
	v_sub_u32_e32 v5, 0, v4
	v_rcp_iflag_f32_e32 v1, v1
	s_nop 0
	v_mul_f32_e32 v1, 0x4f7ffffe, v1
	v_cvt_u32_f32_e32 v1, v1
	v_mul_lo_u32 v5, v5, v1
	v_mul_hi_u32 v5, v1, v5
	v_add_u32_e32 v1, v1, v5
	s_waitcnt vmcnt(0) lgkmcnt(0)
	v_mul_hi_u32 v1, v3, v1
	v_mul_lo_u32 v5, v1, v4
	v_sub_u32_e32 v5, v3, v5
	v_cmp_ge_u32_e32 vcc, v5, v4
	v_add_u32_e32 v6, 1, v1
	v_add_u32_e32 v3, 1, v3
	v_cndmask_b32_e32 v1, v1, v6, vcc
	v_sub_u32_e32 v6, v5, v4
	v_cndmask_b32_e32 v5, v5, v6, vcc
	v_cmp_ge_u32_e32 vcc, v5, v4
	v_add_u32_e32 v5, 1, v1
	s_nop 0
	v_cndmask_b32_e32 v1, v1, v5, vcc
	v_mov_b32_e32 v6, v4
	v_mad_u64_u32 v[4:5], s[4:5], v4, v1, v[4:5]
	v_cmp_ne_u32_e32 vcc, v3, v4
	s_and_saveexec_b64 s[4:5], vcc
	s_xor_b64 s[4:5], exec, s[4:5]
	s_cbranch_execz .LBB0_330
	v_sub_u32_e32 v6, v4, v6
	v_add_u32_e32 v6, 1, v6
	v_cmp_ne_u32_e32 vcc, v3, v6
	s_cbranch_vccnz .Lefl_0
	buffer_wbl2 sc1
.Lefl_0:
	v_mov_b32_e32 v0, s37
	v_add_co_u32_e32 v4, vcc, 0x2000, v0
	v_mov_b32_e32 v0, s36
	s_nop 0
	v_addc_co_u32_e32 v5, vcc, 0, v0, vcc
	flat_load_dword v0, v[4:5] offset:1024 sc1
	s_add_u32 s10, s37, 0x2400
	s_addc_u32 s11, s36, 0
	s_waitcnt vmcnt(0) lgkmcnt(0)
	v_cmp_eq_u32_e32 vcc, v0, v1
	s_and_saveexec_b64 s[6:7], vcc
	s_cbranch_execz .LBB0_329
	s_mov_b32 s38, 1
	s_mov_b64 s[12:13], 0
	s_branch .LBB0_321

; __device__ __forceinline__ unsigned xb_ld(unsigned* p)              { return __hip_atomic_load(p, __ATOMIC_RELAXED, __HIP_MEMORY_SCOPE_AGENT); }
; __device__ __forceinline__ unsigned xb_add(unsigned* p, unsigned v) { return __hip_atomic_fetch_add(p, v, __ATOMIC_RELAXED, __HIP_MEMORY_SCOPE_AGENT); }
; #define XB_SPIN(cond, bar) do { unsigned _sp = 0; while (cond) { __builtin_amdgcn_s_sleep(1); \
;     if ((++_sp & 255u) == 0u) { if (xb_ld(&(bar)[XB_TMO])) break; if (_sp > XB_SPIN_CAP) { atomicAdd(&(bar)[XB_TMO], 1u); break; } } } } while (0)
; __device__ __forceinline__ void xcd_barrier(const XcdBarrier& b) {
;     asm volatile("s_waitcnt vmcnt(0)" ::: "memory");
;     __syncthreads();
;     if (threadIdx.x == 0) {
;         unsigned* bar = b.bar;
;         __builtin_amdgcn_s_waitcnt(0);
;         unsigned nloc = b.st[0], nx = b.st[1];
;         if (nloc == 0u) { xcd_barrier_complete(bar, b.x, nloc, nx); b.st[0] = nloc; b.st[1] = nx; }
;         const unsigned old = xb_add(&bar[XB_XSUB(b.x)], 1u);
;         const unsigned gen = old / nloc;
;         if (old + 1u == (gen + 1u) * nloc) {
;             __builtin_amdgcn_fence(__ATOMIC_RELEASE, "agent");
;             asm volatile("s_waitcnt vmcnt(0)" ::: "memory");
;             const unsigned og = xb_add(&bar[XB_TOP], 1u);
;             const unsigned tg = og / nx;
;             if (og + 1u == (tg + 1u) * nx) xb_add(&bar[XB_TOPGEN], 1u);
;             else XB_SPIN(xb_ld(&bar[XB_TOPGEN]) == tg, bar);
;             __builtin_amdgcn_fence(__ATOMIC_ACQUIRE, "agent");
;             xb_add(&bar[XB_XGEN(b.x)], 1u);
;             asm volatile("s_waitcnt vmcnt(0)" ::: "memory");
;         } else {
;             XB_SPIN(xb_ld(&bar[XB_XGEN(b.x)]) == gen, bar);
.LBB0_1739:
	v_readlane_b32 s4, v253, 44
	s_lshl_b32 s4, s4, 2
	s_add_u32 s36, s2, s4
	s_addc_u32 s8, s3, 0
	v_mov_b32_e32 v1, s36
	v_add_co_u32_e32 v6, vcc, 0x1000, v1
	v_mov_b32_e32 v1, s8
	s_nop 0
	v_addc_co_u32_e32 v7, vcc, 0, v1, vcc
	flat_atomic_add v3, v[6:7], v226 offset:1024 sc0
	v_cvt_f32_u32_e32 v1, v4
	v_sub_u32_e32 v5, 0, v4
	v_rcp_iflag_f32_e32 v1, v1
	s_nop 0
	v_mul_f32_e32 v1, 0x4f7ffffe, v1
	v_cvt_u32_f32_e32 v1, v1
	v_mul_lo_u32 v5, v5, v1
	v_mul_hi_u32 v5, v1, v5
	v_add_u32_e32 v1, v1, v5
	s_waitcnt vmcnt(0) lgkmcnt(0)
	v_mul_hi_u32 v1, v3, v1
	v_mul_lo_u32 v5, v1, v4
	v_sub_u32_e32 v5, v3, v5
	v_cmp_ge_u32_e32 vcc, v5, v4
	v_add_u32_e32 v6, 1, v1
	v_add_u32_e32 v3, 1, v3
	v_cndmask_b32_e32 v1, v1, v6, vcc
	v_sub_u32_e32 v6, v5, v4
	v_cndmask_b32_e32 v5, v5, v6, vcc
	v_cmp_ge_u32_e32 vcc, v5, v4
	v_add_u32_e32 v5, 1, v1
	s_nop 0
	v_cndmask_b32_e32 v1, v1, v5, vcc
	v_mov_b32_e32 v6, v4
	v_mad_u64_u32 v[4:5], s[4:5], v4, v1, v[4:5]
	v_cmp_ne_u32_e32 vcc, v3, v4
	s_and_saveexec_b64 s[4:5], vcc
	s_xor_b64 s[4:5], exec, s[4:5]
	s_cbranch_execz .LBB0_1752
	v_sub_u32_e32 v6, v4, v6
	v_add_u32_e32 v6, 1, v6
	v_cmp_ne_u32_e32 vcc, v3, v6
	s_cbranch_vccnz .Lefl_8
	buffer_wbl2 sc1
.Lefl_8:
	v_mov_b32_e32 v0, s36
	v_add_co_u32_e32 v4, vcc, 0x2000, v0
	v_mov_b32_e32 v0, s8
	s_nop 0
	v_addc_co_u32_e32 v5, vcc, 0, v0, vcc
	flat_load_dword v0, v[4:5] offset:1024 sc1
	s_add_u32 s10, s36, 0x2400
	s_addc_u32 s11, s8, 0
	s_waitcnt vmcnt(0) lgkmcnt(0)
	v_cmp_eq_u32_e32 vcc, v0, v1
	s_and_saveexec_b64 s[6:7], vcc
	s_cbranch_execz .LBB0_1751
	s_mov_b32 s37, 1
	s_mov_b64 s[12:13], 0
	s_branch .LBB0_1743
